# K-loop LDS-DMA issue: address VALU fills the M0 wait state instead of s_nop (18 groups)
# speedup vs baseline: 1.0092x; 1.0092x over previous
; #define LDSR(dst, addr, off) asm volatile("ds_read_b128 %0, %1 offset:%2" : "=&v"(dst) : "v"(addr), "n"(off))
; #define LDSR(dst, addr, off) asm volatile("ds_read_b128 %0, %1 offset:%2" : "=&v"(dst) : "v"(addr), "n"(off))
; template <class AP, class BP, class Epi>
; DI void mfma_gemm_big_tile(const AP& aptr, const BP& bptr, int m0, int n0, int K, const Epi& epi, bf16* lds) {
;     ...
;   BG_ISSUE(0, 0);
;   BG_ISSUE(1, 1);
;   asm volatile("s_waitcnt vmcnt(6)\n\ts_barrier" ::: "memory");
;   const unsigned lbase = (unsigned)(size_t)lds;
;   const unsigned a_off = (unsigned)(((wm + l16) * 32 + (lq ^ ((-(l16 >> 2)) & 3)) * 8) * 2);
;   const unsigned b_off = (unsigned)((256 * 32 + (wn + l16) * 32 + (lq ^ ((-(l16 >> 2)) & 3)) * 8) * 2);
;     ...
;   int cur = 0, nxt = 2;
;   for (int ks = 0; ks < nk; ++ks) {
;     if (ks + 2 < nk) BG_ISSUE(nxt, ks + 2);
;     const unsigned sa = lbase + (unsigned)(cur * BG_STAGE * 2) + a_off, sb = lbase + (unsigned)(cur * BG_STAGE * 2) + b_off;
;     bf16x8 af[8], bfr[4];
;     LDSR(bfr[0], sb, 0); LDSR(bfr[1], sb, 1024); LDSR(bfr[2], sb, 2048); LDSR(bfr[3], sb, 3072);
;     LDSR(af[0], sa, 0); LDSR(af[1], sa, 1024); LDSR(af[2], sa, 2048); LDSR(af[3], sa, 3072);
;     LDSR(af[4], sa, 4096); LDSR(af[5], sa, 5120); LDSR(af[6], sa, 6144); LDSR(af[7], sa, 7168);
.LBB0_250:
	s_mul_i32 s6, s19, 0x6000
	v_add_u32_e32 v145, s6, v143
	v_add_u32_e32 v159, s6, v144
	ds_read_b128 v[146:149], v159 offset:0
	ds_read_b128 v[150:153], v159 offset:0x400
	ds_read_b128 v[154:157], v159 offset:0x800
	ds_read_b128 v[162:165], v159 offset:0xc00
	ds_read_b128 v[166:169], v145 offset:0
	ds_read_b128 v[182:185], v145 offset:0x400
	ds_read_b128 v[192:195], v145 offset:0x800
	ds_read_b128 v[196:199], v145 offset:0xc00
	ds_read_b128 v[200:203], v145 offset:0x1000
	ds_read_b128 v[204:207], v145 offset:0x1400
	ds_read_b128 v[208:211], v145 offset:0x1800
	ds_read_b128 v[212:215], v145 offset:0x1c00
	s_cmp_gt_u32 s16, 29
	s_cselect_b64 s[4:5], -1, 0
	s_and_b64 vcc, exec, s[4:5]
	s_cbranch_vccnz .LBB0_252
	s_mul_i32 s6, s13, 0x6000
	s_add_i32 s6, s18, s6
	s_mov_b32 m0, s6
	v_lshl_add_u64 v[248:249], s[0:1], 1, v[140:141]
	global_load_lds_dwordx4 v[248:249], off
	s_add_i32 m0, s6, 0x1000
	v_lshl_add_u64 v[248:249], s[0:1], 1, v[138:139]
	global_load_lds_dwordx4 v[248:249], off
	s_add_i32 m0, s6, 0x2000
	v_lshl_add_u64 v[248:249], s[0:1], 1, v[136:137]
	global_load_lds_dwordx4 v[248:249], off
	s_add_i32 m0, s6, 0x3000
	v_lshl_add_u64 v[248:249], s[0:1], 1, v[134:135]
	global_load_lds_dwordx4 v[248:249], off
	s_add_i32 m0, s6, 0x4000
	v_lshl_add_u64 v[248:249], s[0:1], 1, v[132:133]
	global_load_lds_dwordx4 v[248:249], off
	s_add_i32 m0, s6, 0x5000
	v_lshl_add_u64 v[248:249], s[0:1], 1, v[130:131]
	global_load_lds_dwordx4 v[248:249], off

; #define LDSR(dst, addr, off) asm volatile("ds_read_b128 %0, %1 offset:%2" : "=&v"(dst) : "v"(addr), "n"(off))
; #define LDSR(dst, addr, off) asm volatile("ds_read_b128 %0, %1 offset:%2" : "=&v"(dst) : "v"(addr), "n"(off))
; template <class AP, class BP, class Epi>
; DI void mfma_gemm_big_tile(const AP& aptr, const BP& bptr, int m0, int n0, int K, const Epi& epi, bf16* lds) {
;     ...
;   BG_ISSUE(0, 0);
;   BG_ISSUE(1, 1);
;   asm volatile("s_waitcnt vmcnt(6)\n\ts_barrier" ::: "memory");
;   const unsigned lbase = (unsigned)(size_t)lds;
;   const unsigned a_off = (unsigned)(((wm + l16) * 32 + (lq ^ ((-(l16 >> 2)) & 3)) * 8) * 2);
;   const unsigned b_off = (unsigned)((256 * 32 + (wn + l16) * 32 + (lq ^ ((-(l16 >> 2)) & 3)) * 8) * 2);
;     ...
;   int cur = 0, nxt = 2;
;   for (int ks = 0; ks < nk; ++ks) {
;     if (ks + 2 < nk) BG_ISSUE(nxt, ks + 2);
;     const unsigned sa = lbase + (unsigned)(cur * BG_STAGE * 2) + a_off, sb = lbase + (unsigned)(cur * BG_STAGE * 2) + b_off;
;     bf16x8 af[8], bfr[4];
;     LDSR(bfr[0], sb, 0); LDSR(bfr[1], sb, 1024); LDSR(bfr[2], sb, 2048); LDSR(bfr[3], sb, 3072);
;     LDSR(af[0], sa, 0); LDSR(af[1], sa, 1024); LDSR(af[2], sa, 2048); LDSR(af[3], sa, 3072);
;     LDSR(af[4], sa, 4096); LDSR(af[5], sa, 5120); LDSR(af[6], sa, 6144); LDSR(af[7], sa, 7168);
.LBB0_510:
	s_mul_i32 s6, s18, 0x6000
	v_add_u32_e32 v145, s6, v143
	v_add_u32_e32 v159, s6, v144
	ds_read_b128 v[146:149], v159 offset:0
	ds_read_b128 v[150:153], v159 offset:0x400
	ds_read_b128 v[154:157], v159 offset:0x800
	ds_read_b128 v[162:165], v159 offset:0xc00
	ds_read_b128 v[166:169], v145 offset:0
	ds_read_b128 v[192:195], v145 offset:0x400
	ds_read_b128 v[196:199], v145 offset:0x800
	ds_read_b128 v[200:203], v145 offset:0xc00
	ds_read_b128 v[204:207], v145 offset:0x1000
	ds_read_b128 v[208:211], v145 offset:0x1400
	ds_read_b128 v[212:215], v145 offset:0x1800
	ds_read_b128 v[216:219], v145 offset:0x1c00
	s_cmp_gt_u32 s15, 29
	s_cselect_b64 s[4:5], -1, 0
	s_and_b64 vcc, exec, s[4:5]
	s_cbranch_vccnz .LBB0_512
	s_mul_i32 s6, s13, 0x6000
	s_add_i32 s6, s17, s6
	s_mov_b32 m0, s6
	v_lshl_add_u64 v[248:249], s[0:1], 1, v[140:141]
	global_load_lds_dwordx4 v[248:249], off
	s_add_i32 m0, s6, 0x1000
	v_lshl_add_u64 v[248:249], s[0:1], 1, v[138:139]
	global_load_lds_dwordx4 v[248:249], off
	s_add_i32 m0, s6, 0x2000
	v_lshl_add_u64 v[248:249], s[0:1], 1, v[136:137]
	global_load_lds_dwordx4 v[248:249], off
	s_add_i32 m0, s6, 0x3000
	v_lshl_add_u64 v[248:249], s[0:1], 1, v[134:135]
	global_load_lds_dwordx4 v[248:249], off
	s_add_i32 m0, s6, 0x4000
	v_lshl_add_u64 v[248:249], s[0:1], 1, v[132:133]
	global_load_lds_dwordx4 v[248:249], off
	s_add_i32 m0, s6, 0x5000
	v_lshl_add_u64 v[248:249], s[0:1], 1, v[130:131]
	global_load_lds_dwordx4 v[248:249], off

; #define LDSR(dst, addr, off) asm volatile("ds_read_b128 %0, %1 offset:%2" : "=&v"(dst) : "v"(addr), "n"(off))
; #define LDSR(dst, addr, off) asm volatile("ds_read_b128 %0, %1 offset:%2" : "=&v"(dst) : "v"(addr), "n"(off))
; template <class AP, class BP, class Epi>
; DI void mfma_gemm_big_tile(const AP& aptr, const BP& bptr, int m0, int n0, int K, const Epi& epi, bf16* lds) {
;     ...
;   BG_ISSUE(0, 0);
;   BG_ISSUE(1, 1);
;   asm volatile("s_waitcnt vmcnt(6)\n\ts_barrier" ::: "memory");
;   const unsigned lbase = (unsigned)(size_t)lds;
;   const unsigned a_off = (unsigned)(((wm + l16) * 32 + (lq ^ ((-(l16 >> 2)) & 3)) * 8) * 2);
;   const unsigned b_off = (unsigned)((256 * 32 + (wn + l16) * 32 + (lq ^ ((-(l16 >> 2)) & 3)) * 8) * 2);
;     ...
;   int cur = 0, nxt = 2;
;   for (int ks = 0; ks < nk; ++ks) {
;     if (ks + 2 < nk) BG_ISSUE(nxt, ks + 2);
;     const unsigned sa = lbase + (unsigned)(cur * BG_STAGE * 2) + a_off, sb = lbase + (unsigned)(cur * BG_STAGE * 2) + b_off;
;     bf16x8 af[8], bfr[4];
;     LDSR(bfr[0], sb, 0); LDSR(bfr[1], sb, 1024); LDSR(bfr[2], sb, 2048); LDSR(bfr[3], sb, 3072);
;     LDSR(af[0], sa, 0); LDSR(af[1], sa, 1024); LDSR(af[2], sa, 2048); LDSR(af[3], sa, 3072);
;     LDSR(af[4], sa, 4096); LDSR(af[5], sa, 5120); LDSR(af[6], sa, 6144); LDSR(af[7], sa, 7168);
.LBB0_1107:
	s_mul_i32 s10, s21, 0x6000
	v_add_u32_e32 v145, s10, v143
	v_add_u32_e32 v159, s10, v144
	ds_read_b128 v[146:149], v159 offset:0
	ds_read_b128 v[150:153], v159 offset:0x400
	ds_read_b128 v[154:157], v159 offset:0x800
	ds_read_b128 v[162:165], v159 offset:0xc00
	ds_read_b128 v[166:169], v145 offset:0
	ds_read_b128 v[182:185], v145 offset:0x400
	ds_read_b128 v[192:195], v145 offset:0x800
	ds_read_b128 v[196:199], v145 offset:0xc00
	ds_read_b128 v[200:203], v145 offset:0x1000
	ds_read_b128 v[204:207], v145 offset:0x1400
	ds_read_b128 v[208:211], v145 offset:0x1800
	ds_read_b128 v[212:215], v145 offset:0x1c00
	s_cmp_gt_u32 s18, 29
	s_cselect_b64 s[8:9], -1, 0
	s_and_b64 vcc, exec, s[8:9]
	s_cbranch_vccnz .LBB0_1109
	s_mul_i32 s10, s17, 0x6000
	s_add_i32 s10, s20, s10
	s_mov_b32 m0, s10
	v_lshl_add_u64 v[248:249], s[0:1], 1, v[140:141]
	global_load_lds_dwordx4 v[248:249], off
	s_add_i32 m0, s10, 0x1000
	v_lshl_add_u64 v[248:249], s[0:1], 1, v[138:139]
	global_load_lds_dwordx4 v[248:249], off
	s_add_i32 m0, s10, 0x2000
	v_lshl_add_u64 v[248:249], s[0:1], 1, v[136:137]
	global_load_lds_dwordx4 v[248:249], off
	s_add_i32 m0, s10, 0x3000
	v_lshl_add_u64 v[248:249], s[0:1], 1, v[134:135]
	global_load_lds_dwordx4 v[248:249], off
	s_add_i32 m0, s10, 0x4000
	v_lshl_add_u64 v[248:249], v[132:133], 0, s[0:1]
	global_load_lds_dwordx4 v[248:249], off
	s_add_i32 m0, s10, 0x5000
	v_lshl_add_u64 v[248:249], v[130:131], 0, s[0:1]
	global_load_lds_dwordx4 v[248:249], off
